# FFN-up K-loop: activation-tile LDS-DMA loads marked nt (weights default)
# baseline (speedup 1.0000x reference)
.LBB0_944:
	s_add_u32 s2, s66, 0xfffc0080
	s_addc_u32 s14, s67, -1
	s_add_i32 s15, 0, 0x10000
	s_cmp_eq_u32 s42, 12
	s_cselect_b32 s27, s18, s14
	s_cselect_b32 s26, s19, s2
	s_cselect_b32 s25, s8, s68
	s_cselect_b32 s24, s57, s61
	s_add_i32 s2, 0, 0x14000
	v_add_u32_e32 v142, s15, v187
	v_add_u32_e32 v170, s2, v187
	ds_read_b128 v[130:133], v142
	ds_read_b128 v[134:137], v142 offset:1024
	ds_read_b128 v[138:141], v142 offset:2048
	ds_read_b128 v[142:145], v142 offset:3072
	ds_read_b128 v[146:149], v170
	ds_read_b128 v[150:153], v170 offset:1024
	ds_read_b128 v[166:169], v170 offset:2048
	ds_read_b128 v[170:173], v170 offset:3072
	v_lshl_add_u64 v[182:183], s[66:67], 0, v[164:165]
	s_add_i32 m0, s47, 0xc000
	ds_read_b128 v[174:177], v191
	ds_read_b128 v[178:181], v191 offset:1024
	ds_read_b128 v[200:203], v191 offset:2048
	ds_read_b128 v[204:207], v191 offset:3072
	ds_read_b128 v[208:211], v191 offset:4096
	ds_read_b128 v[212:215], v191 offset:5120
	ds_read_b128 v[216:219], v191 offset:6144
	ds_read_b128 v[220:223], v191 offset:7168
	global_load_lds_dwordx4 v[182:183], off nt
	v_lshl_add_u64 v[182:183], s[66:67], 0, v[162:163]
	s_add_i32 m0, s47, 0xe000
	s_nop 0
	global_load_lds_dwordx4 v[182:183], off nt
	s_waitcnt vmcnt(8)
	s_waitcnt lgkmcnt(0)
	s_barrier
	s_setprio 1
	s_waitcnt lgkmcnt(0)
	v_mfma_f32_16x16x32_bf16 v[126:129], v[130:133], v[174:177], v[126:129]
	v_mfma_f32_16x16x32_bf16 v[118:121], v[138:141], v[174:177], v[118:121]
	v_mfma_f32_16x16x32_bf16 v[110:113], v[130:133], v[200:203], v[110:113]
	v_mfma_f32_16x16x32_bf16 v[102:105], v[138:141], v[200:203], v[102:105]
	v_mfma_f32_16x16x32_bf16 v[92:95], v[130:133], v[208:211], v[92:95]
	v_mfma_f32_16x16x32_bf16 v[84:87], v[138:141], v[208:211], v[84:87]
	v_mfma_f32_16x16x32_bf16 v[76:79], v[130:133], v[216:219], v[76:79]
	v_mfma_f32_16x16x32_bf16 v[68:71], v[138:141], v[216:219], v[68:71]
	v_mfma_f32_16x16x32_bf16 v[126:129], v[134:137], v[178:181], v[126:129]
	v_mfma_f32_16x16x32_bf16 v[118:121], v[142:145], v[178:181], v[118:121]
	v_mfma_f32_16x16x32_bf16 v[110:113], v[134:137], v[204:207], v[110:113]
	v_mfma_f32_16x16x32_bf16 v[102:105], v[142:145], v[204:207], v[102:105]
	v_mfma_f32_16x16x32_bf16 v[92:95], v[134:137], v[212:215], v[92:95]
	v_mfma_f32_16x16x32_bf16 v[84:87], v[142:145], v[212:215], v[84:87]
	v_mfma_f32_16x16x32_bf16 v[76:79], v[134:137], v[220:223], v[76:79]
	v_mfma_f32_16x16x32_bf16 v[68:71], v[142:145], v[220:223], v[68:71]
	s_setprio 0
	s_setprio 1
	v_mfma_f32_16x16x32_bf16 v[122:125], v[146:149], v[174:177], v[122:125]
	v_mfma_f32_16x16x32_bf16 v[114:117], v[166:169], v[174:177], v[114:117]
	v_mfma_f32_16x16x32_bf16 v[106:109], v[146:149], v[200:203], v[106:109]
	v_mfma_f32_16x16x32_bf16 v[98:101], v[166:169], v[200:203], v[98:101]
	v_mfma_f32_16x16x32_bf16 v[88:91], v[146:149], v[208:211], v[88:91]
	v_mfma_f32_16x16x32_bf16 v[80:83], v[166:169], v[208:211], v[80:83]
	v_mfma_f32_16x16x32_bf16 v[72:75], v[146:149], v[216:219], v[72:75]
	v_mfma_f32_16x16x32_bf16 v[64:67], v[166:169], v[216:219], v[64:67]
	v_mfma_f32_16x16x32_bf16 v[122:125], v[150:153], v[178:181], v[122:125]
	v_mfma_f32_16x16x32_bf16 v[114:117], v[170:173], v[178:181], v[114:117]
	v_mfma_f32_16x16x32_bf16 v[106:109], v[150:153], v[204:207], v[106:109]
	v_mfma_f32_16x16x32_bf16 v[98:101], v[170:173], v[204:207], v[98:101]
	v_mfma_f32_16x16x32_bf16 v[88:91], v[150:153], v[212:215], v[88:91]
	v_mfma_f32_16x16x32_bf16 v[80:83], v[170:173], v[212:215], v[80:83]
	v_mfma_f32_16x16x32_bf16 v[72:75], v[150:153], v[220:223], v[72:75]
	v_mfma_f32_16x16x32_bf16 v[64:67], v[170:173], v[220:223], v[64:67]
	s_setprio 0
	s_barrier
	s_add_i32 s14, s15, s39
	v_lshl_add_u64 v[182:183], s[24:25], 0, v[96:97]
	s_mov_b32 m0, s14
	ds_read_b128 v[174:177], v191 offset:16384
	ds_read_b128 v[178:181], v191 offset:17408
	ds_read_b128 v[200:203], v191 offset:18432
	ds_read_b128 v[204:207], v191 offset:19456
	ds_read_b128 v[208:211], v191 offset:20480
	ds_read_b128 v[212:215], v191 offset:21504
	ds_read_b128 v[216:219], v191 offset:22528
	ds_read_b128 v[220:223], v191 offset:23552
	global_load_lds_dwordx4 v[182:183], off
	s_add_i32 m0, s14, 0x2000
	s_add_u32 s14, s24, 0x40000
	v_lshl_add_u64 v[188:189], s[24:25], 0, v[154:155]
	s_addc_u32 s15, s25, 0
	s_add_i32 s2, s2, s39
	global_load_lds_dwordx4 v[188:189], off
	v_lshl_add_u64 v[192:193], s[14:15], 0, v[96:97]
	s_mov_b32 m0, s2
	v_lshl_add_u64 v[224:225], s[26:27], 0, v[156:157]
	global_load_lds_dwordx4 v[192:193], off
	v_lshl_add_u64 v[192:193], s[14:15], 0, v[154:155]
	s_add_i32 m0, s2, 0x2000
	s_nop 0
	global_load_lds_dwordx4 v[192:193], off
	v_lshl_add_u64 v[192:193], s[26:27], 0, v[158:159]
	s_mov_b32 m0, s47
	s_nop 0
	global_load_lds_dwordx4 v[192:193], off nt
	s_mov_b32 m0, s70
	s_nop 0
	global_load_lds_dwordx4 v[224:225], off nt
	s_waitcnt vmcnt(8)
	s_waitcnt lgkmcnt(0)
	s_barrier
	s_setprio 1
	s_waitcnt lgkmcnt(0)
	v_mfma_f32_16x16x32_bf16 v[60:63], v[130:133], v[174:177], v[60:63]
	v_mfma_f32_16x16x32_bf16 v[52:55], v[138:141], v[174:177], v[52:55]
	v_mfma_f32_16x16x32_bf16 v[44:47], v[130:133], v[200:203], v[44:47]
	v_mfma_f32_16x16x32_bf16 v[36:39], v[138:141], v[200:203], v[36:39]
	v_mfma_f32_16x16x32_bf16 v[28:31], v[130:133], v[208:211], v[28:31]
	v_mfma_f32_16x16x32_bf16 v[20:23], v[138:141], v[208:211], v[20:23]
	v_mfma_f32_16x16x32_bf16 v[12:15], v[130:133], v[216:219], v[12:15]
	v_mfma_f32_16x16x32_bf16 v[4:7], v[138:141], v[216:219], v[4:7]
	v_mfma_f32_16x16x32_bf16 v[60:63], v[134:137], v[178:181], v[60:63]
	v_mfma_f32_16x16x32_bf16 v[52:55], v[142:145], v[178:181], v[52:55]
	v_mfma_f32_16x16x32_bf16 v[44:47], v[134:137], v[204:207], v[44:47]
	v_mfma_f32_16x16x32_bf16 v[36:39], v[142:145], v[204:207], v[36:39]
	v_mfma_f32_16x16x32_bf16 v[28:31], v[134:137], v[212:215], v[28:31]
	v_mfma_f32_16x16x32_bf16 v[20:23], v[142:145], v[212:215], v[20:23]
	v_mfma_f32_16x16x32_bf16 v[12:15], v[134:137], v[220:223], v[12:15]
	v_mfma_f32_16x16x32_bf16 v[4:7], v[142:145], v[220:223], v[4:7]
	s_setprio 0
	s_setprio 1
	v_mfma_f32_16x16x32_bf16 v[56:59], v[146:149], v[174:177], v[56:59]
	v_mfma_f32_16x16x32_bf16 v[48:51], v[166:169], v[174:177], v[48:51]
	v_mfma_f32_16x16x32_bf16 v[40:43], v[146:149], v[200:203], v[40:43]
	v_mfma_f32_16x16x32_bf16 v[32:35], v[166:169], v[200:203], v[32:35]
	v_mfma_f32_16x16x32_bf16 v[24:27], v[146:149], v[208:211], v[24:27]
	v_mfma_f32_16x16x32_bf16 v[16:19], v[166:169], v[208:211], v[16:19]
	v_mfma_f32_16x16x32_bf16 v[8:11], v[146:149], v[216:219], v[8:11]
	v_mfma_f32_16x16x32_bf16 v[0:3], v[166:169], v[216:219], v[0:3]
	v_mfma_f32_16x16x32_bf16 v[56:59], v[150:153], v[178:181], v[56:59]
	v_mfma_f32_16x16x32_bf16 v[48:51], v[170:173], v[178:181], v[48:51]
	v_mfma_f32_16x16x32_bf16 v[40:43], v[150:153], v[204:207], v[40:43]
	v_mfma_f32_16x16x32_bf16 v[32:35], v[170:173], v[204:207], v[32:35]
	v_mfma_f32_16x16x32_bf16 v[24:27], v[150:153], v[212:215], v[24:27]
	v_mfma_f32_16x16x32_bf16 v[16:19], v[170:173], v[212:215], v[16:19]
	v_mfma_f32_16x16x32_bf16 v[8:11], v[150:153], v[220:223], v[8:11]
	v_mfma_f32_16x16x32_bf16 v[0:3], v[170:173], v[220:223], v[0:3]
	s_setprio 0
	s_barrier
	s_add_i32 s2, 0, 0x18000
	s_add_i32 s20, 0, 0x1c000
	v_add_u32_e32 v142, s2, v187
	v_add_u32_e32 v170, s20, v187
	ds_read_b128 v[130:133], v142
	ds_read_b128 v[134:137], v142 offset:1024
	ds_read_b128 v[138:141], v142 offset:2048
	ds_read_b128 v[142:145], v142 offset:3072
	ds_read_b128 v[146:149], v170
	ds_read_b128 v[150:153], v170 offset:1024
	ds_read_b128 v[166:169], v170 offset:2048
	ds_read_b128 v[170:173], v170 offset:3072
	s_add_u32 s14, s26, 0x40000
	s_addc_u32 s15, s27, 0
	s_mov_b32 m0, s71
	v_lshl_add_u64 v[226:227], s[14:15], 0, v[158:159]
	ds_read_b128 v[174:177], v191 offset:32768
	ds_read_b128 v[178:181], v191 offset:33792
	ds_read_b128 v[200:203], v191 offset:34816
	ds_read_b128 v[204:207], v191 offset:35840
	ds_read_b128 v[208:211], v191 offset:36864
	ds_read_b128 v[212:215], v191 offset:37888
	ds_read_b128 v[216:219], v191 offset:38912
	ds_read_b128 v[220:223], v191 offset:39936
	global_load_lds_dwordx4 v[226:227], off nt
	v_lshl_add_u64 v[226:227], s[14:15], 0, v[156:157]
	s_mov_b32 m0, s72
	s_nop 0
	global_load_lds_dwordx4 v[226:227], off nt
	s_waitcnt vmcnt(8)
	s_waitcnt lgkmcnt(0)
	s_barrier
	s_setprio 1
	s_waitcnt lgkmcnt(0)
	v_mfma_f32_16x16x32_bf16 v[126:129], v[130:133], v[174:177], v[126:129]
	v_mfma_f32_16x16x32_bf16 v[118:121], v[138:141], v[174:177], v[118:121]
	v_mfma_f32_16x16x32_bf16 v[110:113], v[130:133], v[200:203], v[110:113]
	v_mfma_f32_16x16x32_bf16 v[102:105], v[138:141], v[200:203], v[102:105]
	v_mfma_f32_16x16x32_bf16 v[92:95], v[130:133], v[208:211], v[92:95]
	v_mfma_f32_16x16x32_bf16 v[84:87], v[138:141], v[208:211], v[84:87]
	v_mfma_f32_16x16x32_bf16 v[76:79], v[130:133], v[216:219], v[76:79]
	v_mfma_f32_16x16x32_bf16 v[68:71], v[138:141], v[216:219], v[68:71]
	v_mfma_f32_16x16x32_bf16 v[126:129], v[134:137], v[178:181], v[126:129]
	v_mfma_f32_16x16x32_bf16 v[118:121], v[142:145], v[178:181], v[118:121]
	v_mfma_f32_16x16x32_bf16 v[110:113], v[134:137], v[204:207], v[110:113]
	v_mfma_f32_16x16x32_bf16 v[102:105], v[142:145], v[204:207], v[102:105]
	v_mfma_f32_16x16x32_bf16 v[92:95], v[134:137], v[212:215], v[92:95]
	v_mfma_f32_16x16x32_bf16 v[84:87], v[142:145], v[212:215], v[84:87]
	v_mfma_f32_16x16x32_bf16 v[76:79], v[134:137], v[220:223], v[76:79]
	v_mfma_f32_16x16x32_bf16 v[68:71], v[142:145], v[220:223], v[68:71]
	s_setprio 0
	s_setprio 1
	v_mfma_f32_16x16x32_bf16 v[122:125], v[146:149], v[174:177], v[122:125]
	v_mfma_f32_16x16x32_bf16 v[114:117], v[166:169], v[174:177], v[114:117]
	v_mfma_f32_16x16x32_bf16 v[106:109], v[146:149], v[200:203], v[106:109]
	v_mfma_f32_16x16x32_bf16 v[98:101], v[166:169], v[200:203], v[98:101]
	v_mfma_f32_16x16x32_bf16 v[88:91], v[146:149], v[208:211], v[88:91]
	v_mfma_f32_16x16x32_bf16 v[80:83], v[166:169], v[208:211], v[80:83]
	v_mfma_f32_16x16x32_bf16 v[72:75], v[146:149], v[216:219], v[72:75]
	v_mfma_f32_16x16x32_bf16 v[64:67], v[166:169], v[216:219], v[64:67]
	v_mfma_f32_16x16x32_bf16 v[122:125], v[150:153], v[178:181], v[122:125]
	v_mfma_f32_16x16x32_bf16 v[114:117], v[170:173], v[178:181], v[114:117]
	v_mfma_f32_16x16x32_bf16 v[106:109], v[150:153], v[204:207], v[106:109]
	v_mfma_f32_16x16x32_bf16 v[98:101], v[170:173], v[204:207], v[98:101]
	v_mfma_f32_16x16x32_bf16 v[88:91], v[150:153], v[212:215], v[88:91]
	v_mfma_f32_16x16x32_bf16 v[80:83], v[170:173], v[212:215], v[80:83]
	v_mfma_f32_16x16x32_bf16 v[72:75], v[150:153], v[220:223], v[72:75]
	v_mfma_f32_16x16x32_bf16 v[64:67], v[170:173], v[220:223], v[64:67]
	s_setprio 0
	s_barrier
	s_add_i32 s2, s2, s39
	v_lshl_add_u64 v[182:183], v[182:183], 0, s[22:23]
	s_mov_b32 m0, s2
	ds_read_b128 v[174:177], v191 offset:49152
	ds_read_b128 v[178:181], v191 offset:50176
	ds_read_b128 v[200:203], v191 offset:51200
	ds_read_b128 v[204:207], v191 offset:52224
	ds_read_b128 v[208:211], v191 offset:53248
	ds_read_b128 v[212:215], v191 offset:54272
	ds_read_b128 v[216:219], v191 offset:55296
	ds_read_b128 v[220:223], v191 offset:56320
	global_load_lds_dwordx4 v[182:183], off
	s_add_i32 m0, s2, 0x2000
	s_add_u32 s14, s24, 0x40080
	v_lshl_add_u64 v[182:183], v[188:189], 0, s[22:23]
	s_addc_u32 s15, s25, 0
	s_add_i32 s2, s20, s39
	global_load_lds_dwordx4 v[182:183], off
	v_lshl_add_u64 v[182:183], s[14:15], 0, v[96:97]
	s_mov_b32 m0, s2
	s_nop 0
	global_load_lds_dwordx4 v[182:183], off
	v_lshl_add_u64 v[182:183], s[14:15], 0, v[154:155]
	s_add_i32 m0, s2, 0x2000
	s_nop 0
	global_load_lds_dwordx4 v[182:183], off
	v_lshl_add_u64 v[182:183], v[192:193], 0, s[22:23]
	s_mov_b32 m0, s73
	s_nop 0
	global_load_lds_dwordx4 v[182:183], off nt
	v_lshl_add_u64 v[182:183], v[224:225], 0, s[22:23]
	s_mov_b32 m0, s74
	s_nop 0
	global_load_lds_dwordx4 v[182:183], off nt
	s_waitcnt vmcnt(8)
	s_waitcnt lgkmcnt(0)
	s_barrier
	s_setprio 1
	s_waitcnt lgkmcnt(0)
	v_mfma_f32_16x16x32_bf16 v[60:63], v[130:133], v[174:177], v[60:63]
	v_mfma_f32_16x16x32_bf16 v[52:55], v[138:141], v[174:177], v[52:55]
	v_mfma_f32_16x16x32_bf16 v[44:47], v[130:133], v[200:203], v[44:47]
	v_mfma_f32_16x16x32_bf16 v[36:39], v[138:141], v[200:203], v[36:39]
	v_mfma_f32_16x16x32_bf16 v[28:31], v[130:133], v[208:211], v[28:31]
	v_mfma_f32_16x16x32_bf16 v[20:23], v[138:141], v[208:211], v[20:23]
	v_mfma_f32_16x16x32_bf16 v[12:15], v[130:133], v[216:219], v[12:15]
	v_mfma_f32_16x16x32_bf16 v[4:7], v[138:141], v[216:219], v[4:7]
	v_mfma_f32_16x16x32_bf16 v[60:63], v[134:137], v[178:181], v[60:63]
	v_mfma_f32_16x16x32_bf16 v[52:55], v[142:145], v[178:181], v[52:55]
	v_mfma_f32_16x16x32_bf16 v[44:47], v[134:137], v[204:207], v[44:47]
	v_mfma_f32_16x16x32_bf16 v[36:39], v[142:145], v[204:207], v[36:39]
	v_mfma_f32_16x16x32_bf16 v[28:31], v[134:137], v[212:215], v[28:31]
	v_mfma_f32_16x16x32_bf16 v[20:23], v[142:145], v[212:215], v[20:23]
	v_mfma_f32_16x16x32_bf16 v[12:15], v[134:137], v[220:223], v[12:15]
	v_mfma_f32_16x16x32_bf16 v[4:7], v[142:145], v[220:223], v[4:7]
	s_setprio 0
	s_setprio 1
	v_mfma_f32_16x16x32_bf16 v[56:59], v[146:149], v[174:177], v[56:59]
	v_mfma_f32_16x16x32_bf16 v[48:51], v[166:169], v[174:177], v[48:51]
	v_mfma_f32_16x16x32_bf16 v[40:43], v[146:149], v[200:203], v[40:43]
	v_mfma_f32_16x16x32_bf16 v[32:35], v[166:169], v[200:203], v[32:35]
	v_mfma_f32_16x16x32_bf16 v[24:27], v[146:149], v[208:211], v[24:27]
	v_mfma_f32_16x16x32_bf16 v[16:19], v[166:169], v[208:211], v[16:19]
	v_mfma_f32_16x16x32_bf16 v[8:11], v[146:149], v[216:219], v[8:11]
	v_mfma_f32_16x16x32_bf16 v[0:3], v[166:169], v[216:219], v[0:3]
	v_mfma_f32_16x16x32_bf16 v[56:59], v[150:153], v[178:181], v[56:59]
	v_mfma_f32_16x16x32_bf16 v[48:51], v[170:173], v[178:181], v[48:51]
	v_mfma_f32_16x16x32_bf16 v[40:43], v[150:153], v[204:207], v[40:43]
	v_mfma_f32_16x16x32_bf16 v[32:35], v[170:173], v[204:207], v[32:35]
	v_mfma_f32_16x16x32_bf16 v[24:27], v[150:153], v[212:215], v[24:27]
	v_mfma_f32_16x16x32_bf16 v[16:19], v[170:173], v[212:215], v[16:19]
	v_mfma_f32_16x16x32_bf16 v[8:11], v[150:153], v[220:223], v[8:11]
	v_mfma_f32_16x16x32_bf16 v[0:3], v[170:173], v[220:223], v[0:3]
	s_setprio 0
	s_barrier
	s_add_i32 s42, s42, 2
	s_add_u32 s61, s61, 0x100
	s_addc_u32 s68, s68, 0
	s_add_u32 s66, s66, 0x100
	s_addc_u32 s67, s67, 0
	s_cmp_gt_u32 s42, 13
	s_cbranch_scc0 .LBB0_944
	v_lshl_add_u32 v180, s4, 8, v185
	v_lshl_add_u32 v199, s60, 8, v185
	v_mov_b32_e32 v251, 0
	v_lshlrev_b32_e32 v250, 6, v199
	v_lshl_add_u64 v[194:195], v[160:161], 0, v[250:251]
	global_load_dwordx4 v[200:203], v[194:195], off
	v_add_u32_e32 v250, 0x10, v199
	v_lshlrev_b32_e32 v250, 6, v250
	v_lshl_add_u64 v[194:195], v[160:161], 0, v[250:251]
	global_load_dwordx4 v[204:207], v[194:195], off
	v_add_u32_e32 v250, 0x20, v199
	v_lshlrev_b32_e32 v250, 6, v250
	v_lshl_add_u64 v[194:195], v[160:161], 0, v[250:251]
	global_load_dwordx4 v[150:153], v[194:195], off
	v_add_u32_e32 v250, 0x30, v199
	v_lshlrev_b32_e32 v250, 6, v250
	v_lshl_add_u64 v[194:195], v[160:161], 0, v[250:251]
	global_load_dwordx4 v[146:149], v[194:195], off
	v_add_u32_e32 v250, 0x80, v199
	v_lshlrev_b32_e32 v250, 6, v250
	v_lshl_add_u64 v[194:195], v[160:161], 0, v[250:251]
	global_load_dwordx4 v[142:145], v[194:195], off
	v_add_u32_e32 v250, 0x90, v199
	v_lshlrev_b32_e32 v250, 6, v250
	v_lshl_add_u64 v[194:195], v[160:161], 0, v[250:251]
	global_load_dwordx4 v[138:141], v[194:195], off
	v_add_u32_e32 v250, 0xa0, v199
	v_lshlrev_b32_e32 v250, 6, v250
	v_lshl_add_u64 v[194:195], v[160:161], 0, v[250:251]
	global_load_dwordx4 v[134:137], v[194:195], off
	v_add_u32_e32 v250, 0xb0, v199
	v_lshlrev_b32_e32 v250, 6, v250
	v_lshl_add_u64 v[194:195], v[160:161], 0, v[250:251]
	global_load_dwordx4 v[130:133], v[194:195], off
	v_or_b32_e32 v178, 16, v180
	v_or_b32_e32 v176, 32, v180
	v_or_b32_e32 v174, 48, v180
	v_add_u32_e32 v172, 0x80, v180
	v_add_u32_e32 v170, 0x90, v180
	v_add_u32_e32 v168, 0xa0, v180
	v_add_u32_e32 v166, 0xb0, v180
	s_and_b64 vcc, exec, s[58:59]
	s_cbranch_vccz .LBB0_947
	s_barrier
